# GDN scan loop read batches deepened from 12 to 14 in the first segment
# baseline (speedup 1.0000x reference)
.LBB0_1067:
	s_bitcmp1_b32 s13, 0
	s_cselect_b32 s10, 0xe000, 0
	v_add_u32_e32 v170, s10, v168
	v_lshlrev_b32_e32 v80, 16, v68
	v_and_b32_e32 v81, 0xffff0000, v68
	v_lshlrev_b32_e32 v64, 16, v144
	v_and_b32_e32 v65, 0xffff0000, v144
	v_lshlrev_b32_e32 v82, 16, v69
	v_and_b32_e32 v83, 0xffff0000, v69
	v_lshlrev_b32_e32 v66, 16, v145
	v_and_b32_e32 v67, 0xffff0000, v145
	v_lshlrev_b32_e32 v84, 16, v70
	v_and_b32_e32 v85, 0xffff0000, v70
	v_lshlrev_b32_e32 v68, 16, v146
	v_and_b32_e32 v69, 0xffff0000, v146
	v_lshlrev_b32_e32 v86, 16, v71
	v_and_b32_e32 v87, 0xffff0000, v71
	v_lshlrev_b32_e32 v70, 16, v147
	v_and_b32_e32 v71, 0xffff0000, v147
	ds_read_b128 v[176:179], v170
	ds_read_b128 v[180:183], v170 offset:1024
	ds_read_b128 v[184:187], v170 offset:2048
	ds_read_b128 v[188:191], v170 offset:3072
	ds_read_b128 v[192:195], v170 offset:4096
	ds_read_b128 v[196:199], v170 offset:5120
	ds_read_b128 v[200:203], v170 offset:6144
	ds_read_b128 v[214:217], v170 offset:7168
	ds_read_b128 v[218:221], v170 offset:8192
	ds_read_b128 v[222:225], v170 offset:9216
	ds_read_b128 v[226:229], v170 offset:10240
	ds_read_b128 v[230:233], v170 offset:11264
	ds_read_b128 v[234:237], v170 offset:12288
	ds_read_b128 v[238:241], v170 offset:13312
	v_lshlrev_b32_e32 v88, 16, v92
	v_and_b32_e32 v89, 0xffff0000, v92
	v_lshlrev_b32_e32 v90, 16, v93
	v_and_b32_e32 v91, 0xffff0000, v93
	v_lshlrev_b32_e32 v92, 16, v94
	v_and_b32_e32 v93, 0xffff0000, v94
	v_lshlrev_b32_e32 v94, 16, v95
	v_and_b32_e32 v95, 0xffff0000, v95
	v_lshlrev_b32_e32 v72, 16, v76
	v_and_b32_e32 v73, 0xffff0000, v76
	s_waitcnt lgkmcnt(13)
	v_mfma_f32_32x32x16_bf16 v[80:95], v[176:179], v[112:115], v[80:95]
	v_lshlrev_b32_e32 v74, 16, v77
	v_and_b32_e32 v75, 0xffff0000, v77
	v_lshlrev_b32_e32 v76, 16, v78
	v_and_b32_e32 v77, 0xffff0000, v78
	v_lshlrev_b32_e32 v78, 16, v79
	v_and_b32_e32 v79, 0xffff0000, v79
	s_waitcnt lgkmcnt(12)
	v_mfma_f32_32x32x16_bf16 v[80:95], v[180:183], v[116:119], v[80:95]
	v_mul_f32_e64 v14, v14, v164
	v_mul_f32_e64 v15, v15, v164
	v_mul_f32_e64 v12, v12, v164
	v_mul_f32_e64 v13, v13, v164
	v_pk_mul_f32 v[10:11], v[10:11], v[164:165] op_sel_hi:[1,0]
	v_pk_mul_f32 v[8:9], v[8:9], v[164:165] op_sel_hi:[1,0]
	v_pk_mul_f32 v[6:7], v[6:7], v[164:165] op_sel_hi:[1,0]
	v_pk_mul_f32 v[4:5], v[4:5], v[164:165] op_sel_hi:[1,0]
	s_waitcnt lgkmcnt(11)
	v_mfma_f32_32x32x16_bf16 v[80:95], v[184:187], v[120:123], v[80:95]
	v_mul_f32_e64 v2, v2, v164
	v_mul_f32_e64 v3, v3, v164
	v_mul_f32_e64 v0, v0, v164
	v_mul_f32_e64 v1, v1, v164
	v_pk_mul_f32 v[30:31], v[30:31], v[164:165] op_sel_hi:[1,0]
	v_pk_mul_f32 v[28:29], v[28:29], v[164:165] op_sel_hi:[1,0]
	v_pk_mul_f32 v[26:27], v[26:27], v[164:165] op_sel_hi:[1,0]
	v_pk_mul_f32 v[24:25], v[24:25], v[164:165] op_sel_hi:[1,0]
	s_waitcnt lgkmcnt(10)
	v_mfma_f32_32x32x16_bf16 v[80:95], v[188:191], v[124:127], v[80:95]
	v_mul_f32_e64 v22, v22, v164
	v_mul_f32_e64 v23, v23, v164
	v_mul_f32_e64 v20, v20, v164
	v_mul_f32_e64 v21, v21, v164
	v_pk_mul_f32 v[18:19], v[18:19], v[164:165] op_sel_hi:[1,0]
	v_pk_mul_f32 v[16:17], v[16:17], v[164:165] op_sel_hi:[1,0]
	v_pk_mul_f32 v[46:47], v[46:47], v[164:165] op_sel_hi:[1,0]
	v_pk_mul_f32 v[44:45], v[44:45], v[164:165] op_sel_hi:[1,0]
	s_waitcnt lgkmcnt(9)
	v_mfma_f32_32x32x16_bf16 v[80:95], v[192:195], v[128:131], v[80:95]
	v_mul_f32_e64 v42, v42, v164
	v_mul_f32_e64 v43, v43, v164
	v_mul_f32_e64 v40, v40, v164
	v_mul_f32_e64 v41, v41, v164
	v_pk_mul_f32 v[38:39], v[38:39], v[164:165] op_sel_hi:[1,0]
	v_pk_mul_f32 v[36:37], v[36:37], v[164:165] op_sel_hi:[1,0]
	v_pk_mul_f32 v[34:35], v[34:35], v[164:165] op_sel_hi:[1,0]
	v_pk_mul_f32 v[32:33], v[32:33], v[164:165] op_sel_hi:[1,0]
	s_waitcnt lgkmcnt(8)
	v_mfma_f32_32x32x16_bf16 v[80:95], v[196:199], v[132:135], v[80:95]
	v_mul_f32_e64 v62, v62, v164
	v_mul_f32_e64 v63, v63, v164
	v_mul_f32_e64 v60, v60, v164
	v_mul_f32_e64 v61, v61, v164
	v_pk_mul_f32 v[58:59], v[58:59], v[164:165] op_sel_hi:[1,0]
	v_pk_mul_f32 v[56:57], v[56:57], v[164:165] op_sel_hi:[1,0]
	v_pk_mul_f32 v[54:55], v[54:55], v[164:165] op_sel_hi:[1,0]
	v_pk_mul_f32 v[52:53], v[52:53], v[164:165] op_sel_hi:[1,0]
	s_waitcnt lgkmcnt(7)
	v_mfma_f32_32x32x16_bf16 v[80:95], v[200:203], v[136:139], v[80:95]
	v_mul_f32_e64 v50, v50, v164
	v_mul_f32_e64 v51, v51, v164
	v_mul_f32_e64 v48, v48, v164
	v_mul_f32_e64 v49, v49, v164
	s_waitcnt lgkmcnt(6)
	v_mfma_f32_32x32x16_bf16 v[80:95], v[214:217], v[140:143], v[80:95]
	s_waitcnt lgkmcnt(5)
	v_mfma_f32_32x32x16_bf16 v[64:79], v[218:221], v[112:115], v[64:79]
	s_waitcnt lgkmcnt(4)
	v_mfma_f32_32x32x16_bf16 v[64:79], v[222:225], v[116:119], v[64:79]
	s_waitcnt lgkmcnt(3)
	v_mfma_f32_32x32x16_bf16 v[64:79], v[226:229], v[120:123], v[64:79]
	s_waitcnt lgkmcnt(2)
	v_mfma_f32_32x32x16_bf16 v[64:79], v[230:233], v[124:127], v[64:79]
	s_waitcnt lgkmcnt(1)
	v_mfma_f32_32x32x16_bf16 v[64:79], v[234:237], v[128:131], v[64:79]
	s_waitcnt lgkmcnt(0)
	v_mfma_f32_32x32x16_bf16 v[64:79], v[238:241], v[132:135], v[64:79]
	ds_read_b128 v[176:179], v170 offset:14336
	ds_read_b128 v[180:183], v170 offset:32768
	ds_read_b128 v[184:187], v170 offset:17408
	ds_read_b128 v[188:191], v170 offset:33792
	ds_read_b128 v[192:195], v170 offset:34816
	ds_read_b128 v[196:199], v170 offset:35840
	ds_read_b128 v[200:203], v170 offset:36864
	ds_read_b128 v[214:217], v170 offset:37888
	ds_read_b128 v[218:221], v170 offset:38912
	ds_read_b128 v[222:225], v170 offset:39936
	ds_read_b128 v[226:229], v170 offset:40960
	ds_read_b128 v[230:233], v170 offset:41984
	ds_read_b128 v[234:237], v170 offset:43008
	ds_read_b128 v[238:241], v170 offset:44032
	s_waitcnt lgkmcnt(13)
	v_mfma_f32_32x32x16_bf16 v[64:79], v[176:179], v[136:139], v[64:79]
	ds_read_b128 v[144:147], v170 offset:15360
	s_waitcnt lgkmcnt(0)
	v_mfma_f32_32x32x16_bf16 v[64:79], v[144:147], v[140:143], v[64:79]
	v_cvt_pk_bf16_f32 v144, v80, v81
	v_cvt_pk_bf16_f32 v145, v82, v83
	v_cvt_pk_bf16_f32 v146, v84, v85
	v_cvt_pk_bf16_f32 v147, v86, v87
	v_cvt_pk_bf16_f32 v80, v88, v89
	v_cvt_pk_bf16_f32 v81, v90, v91
	v_cvt_pk_bf16_f32 v82, v92, v93
	v_cvt_pk_bf16_f32 v83, v94, v95
	v_cvt_pk_bf16_f32 v88, v64, v65
	v_cvt_pk_bf16_f32 v89, v66, v67
	v_cvt_pk_bf16_f32 v90, v68, v69
	v_cvt_pk_bf16_f32 v91, v70, v71
	v_cvt_pk_bf16_f32 v84, v72, v73
	v_cvt_pk_bf16_f32 v85, v74, v75
	v_cvt_pk_bf16_f32 v86, v76, v77
	v_cvt_pk_bf16_f32 v87, v78, v79
	s_nop 11
	s_waitcnt lgkmcnt(0)
	v_mfma_f32_32x32x16_bf16 v[0:15], v[180:183], v[144:147], v[0:15]
	v_mov_b32_e32 v93, 0
	v_add_u32_e32 v92, s12, v149
	s_waitcnt lgkmcnt(0)
	v_mfma_f32_32x32x16_bf16 v[0:15], v[188:191], v[80:83], v[0:15]
	s_waitcnt lgkmcnt(0)
	v_mfma_f32_32x32x16_bf16 v[0:15], v[192:195], v[88:91], v[0:15]
	s_waitcnt lgkmcnt(0)
	v_mfma_f32_32x32x16_bf16 v[0:15], v[196:199], v[84:87], v[0:15]
	s_waitcnt lgkmcnt(0)
	v_mfma_f32_32x32x16_bf16 v[16:31], v[200:203], v[144:147], v[16:31]
	s_waitcnt lgkmcnt(0)
	v_mfma_f32_32x32x16_bf16 v[16:31], v[214:217], v[80:83], v[16:31]
	s_waitcnt lgkmcnt(0)
	v_mfma_f32_32x32x16_bf16 v[16:31], v[218:221], v[88:91], v[16:31]
	s_waitcnt lgkmcnt(0)
	v_mfma_f32_32x32x16_bf16 v[16:31], v[222:225], v[84:87], v[16:31]
	s_waitcnt lgkmcnt(0)
	v_mfma_f32_32x32x16_bf16 v[32:47], v[226:229], v[144:147], v[32:47]
	s_waitcnt lgkmcnt(0)
	v_mfma_f32_32x32x16_bf16 v[32:47], v[230:233], v[80:83], v[32:47]
	s_waitcnt lgkmcnt(0)
	v_mfma_f32_32x32x16_bf16 v[32:47], v[234:237], v[88:91], v[32:47]
	s_waitcnt lgkmcnt(0)
	v_mfma_f32_32x32x16_bf16 v[32:47], v[238:241], v[84:87], v[32:47]
	ds_read_b128 v[176:179], v170 offset:45056
	ds_read_b128 v[180:183], v170 offset:46080
	ds_read_b128 v[188:191], v170 offset:47104
	ds_read_b128 v[192:195], v170 offset:48128
	ds_read_b128 v[196:199], v170 offset:18432
	ds_read_b128 v[200:203], v170 offset:19456
	ds_read_b128 v[214:217], v170 offset:20480
	ds_read_b128 v[218:221], v170 offset:21504
	ds_read_b128 v[222:225], v170 offset:22528
	ds_read_b128 v[226:229], v170 offset:23552
	ds_read_b128 v[230:233], v170 offset:49152
	ds_read_b128 v[234:237], v170 offset:50176
	ds_read_b128 v[238:241], v170 offset:51200
	s_waitcnt lgkmcnt(12)
	v_mfma_f32_32x32x16_bf16 v[48:63], v[176:179], v[144:147], v[48:63]
	s_waitcnt lgkmcnt(11)
	v_mfma_f32_32x32x16_bf16 v[48:63], v[180:183], v[80:83], v[48:63]
	s_waitcnt lgkmcnt(10)
	v_mfma_f32_32x32x16_bf16 v[48:63], v[188:191], v[88:91], v[48:63]
	s_waitcnt lgkmcnt(9)
	v_mfma_f32_32x32x16_bf16 v[48:63], v[192:195], v[84:87], v[48:63]
	ds_read_b128 v[64:67], v170 offset:16384
	s_waitcnt lgkmcnt(0)
	v_mfma_f32_32x32x16_bf16 v[64:79], v[64:67], v[112:115], 0
	v_mfma_f32_32x32x16_bf16 v[64:79], v[184:187], v[116:119], v[64:79]
	s_waitcnt lgkmcnt(0)
	v_mfma_f32_32x32x16_bf16 v[64:79], v[196:199], v[120:123], v[64:79]
	s_waitcnt lgkmcnt(0)
	v_mfma_f32_32x32x16_bf16 v[64:79], v[200:203], v[124:127], v[64:79]
	s_waitcnt lgkmcnt(0)
	v_mfma_f32_32x32x16_bf16 v[64:79], v[214:217], v[128:131], v[64:79]
	s_waitcnt lgkmcnt(0)
	v_mfma_f32_32x32x16_bf16 v[64:79], v[218:221], v[132:135], v[64:79]
	s_waitcnt lgkmcnt(0)
	v_mfma_f32_32x32x16_bf16 v[64:79], v[222:225], v[136:139], v[64:79]
	s_waitcnt lgkmcnt(0)
	v_mfma_f32_32x32x16_bf16 v[64:79], v[226:229], v[140:143], v[64:79]
	s_waitcnt lgkmcnt(0)
	v_mfma_f32_32x32x16_bf16 v[64:79], v[230:233], v[144:147], v[64:79]
	s_waitcnt lgkmcnt(0)
	v_mfma_f32_32x32x16_bf16 v[64:79], v[234:237], v[80:83], v[64:79]
	s_waitcnt lgkmcnt(0)
	v_mfma_f32_32x32x16_bf16 v[64:79], v[238:241], v[88:91], v[64:79]
	ds_read_b128 v[172:175], v170 offset:52224
	s_waitcnt lgkmcnt(0)
	v_mfma_f32_32x32x16_bf16 v[64:79], v[172:175], v[84:87], v[64:79]
	s_nop 11
	v_mov_b32_dpp v93, v64 quad_perm:[1,0,3,2] row_mask:0xf bank_mask:0xf
	s_and_saveexec_b64 s[10:11], vcc
	s_cbranch_execz .LBB0_1069
	v_bfe_u32 v94, v64, 16, 1
	s_movk_i32 s14, 0x7fff
	v_add3_u32 v64, v64, v94, s14
	v_bfe_u32 v94, v93, 16, 1
	v_lshrrev_b32_e32 v64, 16, v64
	v_add3_u32 v93, v93, v94, s14
	s_mov_b32 s14, 0xffff0000
	v_and_or_b32 v64, v93, s14, v64
	s_movk_i32 s14, 0x600
	v_mad_i64_i32 v[94:95], s[14:15], v92, s14, v[150:151]
	global_store_dword v[94:95], v64, off
